# pooling mixer: window accumulation with scalar v_add_f32 pairs instead of v_pk_add_f32
# speedup vs baseline: 1.0019x; 1.0019x over previous
.Lp2_ld19:
	s_waitcnt vmcnt(0)
	v_lshlrev_b32_e32 v2, 16, v6
	v_and_b32_e32 v3, 0xffff0000, v6
	v_lshlrev_b32_e32 v4, 16, v7
	v_and_b32_e32 v5, 0xffff0000, v7
	v_lshlrev_b32_e32 v6, 16, v8
	v_and_b32_e32 v7, 0xffff0000, v8
	v_lshlrev_b32_e32 v8, 16, v9
	v_and_b32_e32 v9, 0xffff0000, v9
	v_lshlrev_b32_e32 v10, 16, v14
	v_and_b32_e32 v11, 0xffff0000, v14
	v_lshlrev_b32_e32 v12, 16, v15
	v_and_b32_e32 v13, 0xffff0000, v15
	v_lshlrev_b32_e32 v14, 16, v16
	v_and_b32_e32 v15, 0xffff0000, v16
	v_lshlrev_b32_e32 v16, 16, v17
	v_and_b32_e32 v17, 0xffff0000, v17
	v_lshlrev_b32_e32 v18, 16, v22
	v_and_b32_e32 v19, 0xffff0000, v22
	v_lshlrev_b32_e32 v20, 16, v23
	v_and_b32_e32 v21, 0xffff0000, v23
	v_lshlrev_b32_e32 v22, 16, v24
	v_and_b32_e32 v23, 0xffff0000, v24
	v_lshlrev_b32_e32 v24, 16, v25
	v_and_b32_e32 v25, 0xffff0000, v25
	v_lshlrev_b32_e32 v26, 16, v30
	v_and_b32_e32 v27, 0xffff0000, v30
	v_lshlrev_b32_e32 v28, 16, v31
	v_and_b32_e32 v29, 0xffff0000, v31
	v_lshlrev_b32_e32 v30, 16, v32
	v_and_b32_e32 v31, 0xffff0000, v32
	v_lshlrev_b32_e32 v32, 16, v33
	v_and_b32_e32 v33, 0xffff0000, v33
	v_lshlrev_b32_e32 v34, 16, v38
	v_and_b32_e32 v35, 0xffff0000, v38
	v_lshlrev_b32_e32 v36, 16, v39
	v_and_b32_e32 v37, 0xffff0000, v39
	v_lshlrev_b32_e32 v38, 16, v40
	v_and_b32_e32 v39, 0xffff0000, v40
	v_lshlrev_b32_e32 v40, 16, v41
	v_and_b32_e32 v41, 0xffff0000, v41
	v_lshlrev_b32_e32 v42, 16, v46
	v_and_b32_e32 v43, 0xffff0000, v46
	v_lshlrev_b32_e32 v44, 16, v47
	v_and_b32_e32 v45, 0xffff0000, v47
	v_lshlrev_b32_e32 v46, 16, v48
	v_and_b32_e32 v47, 0xffff0000, v48
	v_lshlrev_b32_e32 v48, 16, v49
	v_and_b32_e32 v49, 0xffff0000, v49
	v_lshlrev_b32_e32 v50, 16, v54
	v_and_b32_e32 v51, 0xffff0000, v54
	v_lshlrev_b32_e32 v52, 16, v55
	v_and_b32_e32 v53, 0xffff0000, v55
	v_lshlrev_b32_e32 v54, 16, v56
	v_and_b32_e32 v55, 0xffff0000, v56
	v_lshlrev_b32_e32 v56, 16, v57
	v_and_b32_e32 v57, 0xffff0000, v57
	v_lshlrev_b32_e32 v58, 16, v62
	v_and_b32_e32 v59, 0xffff0000, v62
	v_lshlrev_b32_e32 v60, 16, v63
	v_and_b32_e32 v61, 0xffff0000, v63
	v_lshlrev_b32_e32 v62, 16, v64
	v_and_b32_e32 v63, 0xffff0000, v64
	v_lshlrev_b32_e32 v64, 16, v65
	v_and_b32_e32 v65, 0xffff0000, v65
	v_lshlrev_b32_e32 v66, 16, v70
	v_and_b32_e32 v67, 0xffff0000, v70
	v_lshlrev_b32_e32 v68, 16, v71
	v_and_b32_e32 v69, 0xffff0000, v71
	v_lshlrev_b32_e32 v70, 16, v72
	v_and_b32_e32 v71, 0xffff0000, v72
	v_lshlrev_b32_e32 v72, 16, v73
	v_and_b32_e32 v73, 0xffff0000, v73
	v_lshlrev_b32_e32 v74, 16, v78
	v_and_b32_e32 v75, 0xffff0000, v78
	v_lshlrev_b32_e32 v76, 16, v79
	v_and_b32_e32 v77, 0xffff0000, v79
	v_lshlrev_b32_e32 v78, 16, v80
	v_and_b32_e32 v79, 0xffff0000, v80
	v_lshlrev_b32_e32 v80, 16, v81
	v_and_b32_e32 v81, 0xffff0000, v81
	v_lshlrev_b32_e32 v82, 16, v86
	v_and_b32_e32 v83, 0xffff0000, v86
	v_lshlrev_b32_e32 v84, 16, v87
	v_and_b32_e32 v85, 0xffff0000, v87
	v_lshlrev_b32_e32 v86, 16, v88
	v_and_b32_e32 v87, 0xffff0000, v88
	v_lshlrev_b32_e32 v88, 16, v89
	v_and_b32_e32 v89, 0xffff0000, v89
	v_lshlrev_b32_e32 v90, 16, v94
	v_and_b32_e32 v91, 0xffff0000, v94
	v_lshlrev_b32_e32 v92, 16, v95
	v_and_b32_e32 v93, 0xffff0000, v95
	v_lshlrev_b32_e32 v94, 16, v96
	v_and_b32_e32 v95, 0xffff0000, v96
	v_lshlrev_b32_e32 v96, 16, v97
	v_and_b32_e32 v97, 0xffff0000, v97
	v_lshlrev_b32_e32 v98, 16, v102
	v_and_b32_e32 v99, 0xffff0000, v102
	v_lshlrev_b32_e32 v100, 16, v103
	v_and_b32_e32 v101, 0xffff0000, v103
	v_lshlrev_b32_e32 v102, 16, v104
	v_and_b32_e32 v103, 0xffff0000, v104
	v_lshlrev_b32_e32 v104, 16, v105
	v_and_b32_e32 v105, 0xffff0000, v105
	v_lshlrev_b32_e32 v106, 16, v110
	v_and_b32_e32 v107, 0xffff0000, v110
	v_lshlrev_b32_e32 v108, 16, v111
	v_and_b32_e32 v109, 0xffff0000, v111
	v_lshlrev_b32_e32 v110, 16, v112
	v_and_b32_e32 v111, 0xffff0000, v112
	v_lshlrev_b32_e32 v112, 16, v113
	v_and_b32_e32 v113, 0xffff0000, v113
	v_lshlrev_b32_e32 v114, 16, v118
	v_and_b32_e32 v115, 0xffff0000, v118
	v_lshlrev_b32_e32 v116, 16, v119
	v_and_b32_e32 v117, 0xffff0000, v119
	v_lshlrev_b32_e32 v118, 16, v120
	v_and_b32_e32 v119, 0xffff0000, v120
	v_lshlrev_b32_e32 v120, 16, v121
	v_and_b32_e32 v121, 0xffff0000, v121
	v_lshlrev_b32_e32 v122, 16, v126
	v_and_b32_e32 v123, 0xffff0000, v126
	v_lshlrev_b32_e32 v124, 16, v127
	v_and_b32_e32 v125, 0xffff0000, v127
	v_lshlrev_b32_e32 v126, 16, v128
	v_and_b32_e32 v127, 0xffff0000, v128
	v_lshlrev_b32_e32 v128, 16, v129
	v_and_b32_e32 v129, 0xffff0000, v129
	v_lshlrev_b32_e32 v130, 16, v134
	v_and_b32_e32 v131, 0xffff0000, v134
	v_lshlrev_b32_e32 v132, 16, v135
	v_and_b32_e32 v133, 0xffff0000, v135
	v_lshlrev_b32_e32 v134, 16, v136
	v_and_b32_e32 v135, 0xffff0000, v136
	v_lshlrev_b32_e32 v136, 16, v137
	v_and_b32_e32 v137, 0xffff0000, v137
	v_lshlrev_b32_e32 v138, 16, v142
	v_and_b32_e32 v139, 0xffff0000, v142
	v_lshlrev_b32_e32 v140, 16, v143
	v_and_b32_e32 v141, 0xffff0000, v143
	v_lshlrev_b32_e32 v142, 16, v144
	v_and_b32_e32 v143, 0xffff0000, v144
	v_lshlrev_b32_e32 v144, 16, v145
	v_and_b32_e32 v145, 0xffff0000, v145
	v_lshlrev_b32_e32 v146, 16, v150
	v_and_b32_e32 v147, 0xffff0000, v150
	v_lshlrev_b32_e32 v148, 16, v151
	v_and_b32_e32 v149, 0xffff0000, v151
	v_lshlrev_b32_e32 v150, 16, v152
	v_and_b32_e32 v151, 0xffff0000, v152
	v_lshlrev_b32_e32 v152, 16, v153
	v_and_b32_e32 v153, 0xffff0000, v153
	v_mov_b32_e32 v212, 0
	v_mov_b32_e32 v213, 0
	v_mov_b32_e32 v214, 0
	v_mov_b32_e32 v215, 0
	v_mov_b32_e32 v216, 0
	v_mov_b32_e32 v217, 0
	v_mov_b32_e32 v218, 0
	v_mov_b32_e32 v219, 0
	s_add_i32 s15, s14, -8
	s_cmp_lt_u32 s15, s13
	s_cbranch_scc0 .Lp2_rw20
	s_mov_b64 exec, s[38:39]
	v_add_f32_e32 v212, v212, v2
	v_add_f32_e32 v213, v213, v3
	v_add_f32_e32 v214, v214, v4
	v_add_f32_e32 v215, v215, v5
	v_add_f32_e32 v216, v216, v6
	v_add_f32_e32 v217, v217, v7
	v_add_f32_e32 v218, v218, v8
	v_add_f32_e32 v219, v219, v9
.Lp2_rw20:
	s_add_i32 s15, s14, -7
	s_cmp_lt_u32 s15, s13
	s_cbranch_scc0 .Lp2_rw21
	s_mov_b64 exec, s[38:39]
	v_add_f32_e32 v212, v212, v10
	v_add_f32_e32 v213, v213, v11
	v_add_f32_e32 v214, v214, v12
	v_add_f32_e32 v215, v215, v13
	v_add_f32_e32 v216, v216, v14
	v_add_f32_e32 v217, v217, v15
	v_add_f32_e32 v218, v218, v16
	v_add_f32_e32 v219, v219, v17
.Lp2_rw21:
	s_add_i32 s15, s14, -6
	s_cmp_lt_u32 s15, s13
	s_cbranch_scc0 .Lp2_rw22
	s_mov_b64 exec, s[38:39]
	v_add_f32_e32 v212, v212, v18
	v_add_f32_e32 v213, v213, v19
	v_add_f32_e32 v214, v214, v20
	v_add_f32_e32 v215, v215, v21
	v_add_f32_e32 v216, v216, v22
	v_add_f32_e32 v217, v217, v23
	v_add_f32_e32 v218, v218, v24
	v_add_f32_e32 v219, v219, v25
.Lp2_rw22:
	s_add_i32 s15, s14, -5
	s_cmp_lt_u32 s15, s13
	s_cbranch_scc0 .Lp2_rw23
	s_mov_b64 exec, s[38:39]
	v_add_f32_e32 v212, v212, v26
	v_add_f32_e32 v213, v213, v27
	v_add_f32_e32 v214, v214, v28
	v_add_f32_e32 v215, v215, v29
	v_add_f32_e32 v216, v216, v30
	v_add_f32_e32 v217, v217, v31
	v_add_f32_e32 v218, v218, v32
	v_add_f32_e32 v219, v219, v33
.Lp2_rw23:
	s_add_i32 s15, s14, -4
	s_cmp_lt_u32 s15, s13
	s_cbranch_scc0 .Lp2_rw24
	s_mov_b64 exec, s[10:11]
	v_add_f32_e32 v212, v212, v34
	v_add_f32_e32 v213, v213, v35
	v_add_f32_e32 v214, v214, v36
	v_add_f32_e32 v215, v215, v37
	v_add_f32_e32 v216, v216, v38
	v_add_f32_e32 v217, v217, v39
	v_add_f32_e32 v218, v218, v40
	v_add_f32_e32 v219, v219, v41
.Lp2_rw24:
	s_add_i32 s15, s14, -3
	s_cmp_lt_u32 s15, s13
	s_cbranch_scc0 .Lp2_rw25
	s_mov_b64 exec, s[10:11]
	v_add_f32_e32 v212, v212, v42
	v_add_f32_e32 v213, v213, v43
	v_add_f32_e32 v214, v214, v44
	v_add_f32_e32 v215, v215, v45
	v_add_f32_e32 v216, v216, v46
	v_add_f32_e32 v217, v217, v47
	v_add_f32_e32 v218, v218, v48
	v_add_f32_e32 v219, v219, v49
.Lp2_rw25:
	s_add_i32 s15, s14, -2
	s_cmp_lt_u32 s15, s13
	s_cbranch_scc0 .Lp2_rw26
	s_mov_b64 exec, s[8:9]
	v_add_f32_e32 v212, v212, v50
	v_add_f32_e32 v213, v213, v51
	v_add_f32_e32 v214, v214, v52
	v_add_f32_e32 v215, v215, v53
	v_add_f32_e32 v216, v216, v54
	v_add_f32_e32 v217, v217, v55
	v_add_f32_e32 v218, v218, v56
	v_add_f32_e32 v219, v219, v57
.Lp2_rw26:
	s_add_i32 s15, s14, -1
	s_cmp_lt_u32 s15, s13
	s_cbranch_scc0 .Lp2_rw27
	s_mov_b64 exec, -1
	v_add_f32_e32 v212, v212, v58
	v_add_f32_e32 v213, v213, v59
	v_add_f32_e32 v214, v214, v60
	v_add_f32_e32 v215, v215, v61
	v_add_f32_e32 v216, v216, v62
	v_add_f32_e32 v217, v217, v63
	v_add_f32_e32 v218, v218, v64
	v_add_f32_e32 v219, v219, v65
.Lp2_rw27:
	s_add_i32 s15, s14, 0
	s_cmp_lt_u32 s15, s13
	s_cbranch_scc0 .Lp2_rw28
	s_mov_b64 exec, -1
	v_add_f32_e32 v212, v212, v66
	v_add_f32_e32 v213, v213, v67
	v_add_f32_e32 v214, v214, v68
	v_add_f32_e32 v215, v215, v69
	v_add_f32_e32 v216, v216, v70
	v_add_f32_e32 v217, v217, v71
	v_add_f32_e32 v218, v218, v72
	v_add_f32_e32 v219, v219, v73
.Lp2_rw28:
	s_add_i32 s15, s14, 1
	s_cmp_lt_u32 s15, s13
	s_cbranch_scc0 .Lp2_rw29
	s_mov_b64 exec, s[8:9]
	v_add_f32_e32 v212, v212, v74
	v_add_f32_e32 v213, v213, v75
	v_add_f32_e32 v214, v214, v76
	v_add_f32_e32 v215, v215, v77
	v_add_f32_e32 v216, v216, v78
	v_add_f32_e32 v217, v217, v79
	v_add_f32_e32 v218, v218, v80
	v_add_f32_e32 v219, v219, v81
.Lp2_rw29:
	s_add_i32 s15, s14, 2
	s_cmp_lt_u32 s15, s13
	s_cbranch_scc0 .Lp2_rw30
	s_mov_b64 exec, s[10:11]
	v_add_f32_e32 v212, v212, v82
	v_add_f32_e32 v213, v213, v83
	v_add_f32_e32 v214, v214, v84
	v_add_f32_e32 v215, v215, v85
	v_add_f32_e32 v216, v216, v86
	v_add_f32_e32 v217, v217, v87
	v_add_f32_e32 v218, v218, v88
	v_add_f32_e32 v219, v219, v89
.Lp2_rw30:
	s_add_i32 s15, s14, 3
	s_cmp_lt_u32 s15, s13
	s_cbranch_scc0 .Lp2_rw31
	s_mov_b64 exec, s[10:11]
	v_add_f32_e32 v212, v212, v90
	v_add_f32_e32 v213, v213, v91
	v_add_f32_e32 v214, v214, v92
	v_add_f32_e32 v215, v215, v93
	v_add_f32_e32 v216, v216, v94
	v_add_f32_e32 v217, v217, v95
	v_add_f32_e32 v218, v218, v96
	v_add_f32_e32 v219, v219, v97
.Lp2_rw31:
	s_add_i32 s15, s14, 4
	s_cmp_lt_u32 s15, s13
	s_cbranch_scc0 .Lp2_rw32
	s_mov_b64 exec, s[38:39]
	v_add_f32_e32 v212, v212, v98
	v_add_f32_e32 v213, v213, v99
	v_add_f32_e32 v214, v214, v100
	v_add_f32_e32 v215, v215, v101
	v_add_f32_e32 v216, v216, v102
	v_add_f32_e32 v217, v217, v103
	v_add_f32_e32 v218, v218, v104
	v_add_f32_e32 v219, v219, v105
.Lp2_rw32:
	s_add_i32 s15, s14, 5
	s_cmp_lt_u32 s15, s13
	s_cbranch_scc0 .Lp2_rw33
	s_mov_b64 exec, s[38:39]
	v_add_f32_e32 v212, v212, v106
	v_add_f32_e32 v213, v213, v107
	v_add_f32_e32 v214, v214, v108
	v_add_f32_e32 v215, v215, v109
	v_add_f32_e32 v216, v216, v110
	v_add_f32_e32 v217, v217, v111
	v_add_f32_e32 v218, v218, v112
	v_add_f32_e32 v219, v219, v113
.Lp2_rw33:
	s_add_i32 s15, s14, 6
	s_cmp_lt_u32 s15, s13
	s_cbranch_scc0 .Lp2_rw34
	s_mov_b64 exec, s[38:39]
	v_add_f32_e32 v212, v212, v114
	v_add_f32_e32 v213, v213, v115
	v_add_f32_e32 v214, v214, v116
	v_add_f32_e32 v215, v215, v117
	v_add_f32_e32 v216, v216, v118
	v_add_f32_e32 v217, v217, v119
	v_add_f32_e32 v218, v218, v120
	v_add_f32_e32 v219, v219, v121
.Lp2_rw34:
	s_add_i32 s15, s14, 7
	s_cmp_lt_u32 s15, s13
	s_cbranch_scc0 .Lp2_rw35
	s_mov_b64 exec, s[38:39]
	v_add_f32_e32 v212, v212, v122
	v_add_f32_e32 v213, v213, v123
	v_add_f32_e32 v214, v214, v124
	v_add_f32_e32 v215, v215, v125
	v_add_f32_e32 v216, v216, v126
	v_add_f32_e32 v217, v217, v127
	v_add_f32_e32 v218, v218, v128
	v_add_f32_e32 v219, v219, v129
.Lp2_rw35:
	s_mov_b64 exec, -1
	s_add_i32 s15, s14, 0
	v_sub_u32_e32 v247, s15, v245
	v_max_i32_e32 v247, 0, v247
	v_add_u32_e32 v248, s15, v245
	v_min_i32_e32 v248, s13, v248
	v_sub_u32_e32 v249, v248, v247
	v_cvt_f32_i32_e32 v154, v249
	v_div_scale_f32 v155, s[2:3], v154, v154, 1.0
	v_rcp_f32_e32 v156, v155
	s_nop 0
	v_fma_f32 v157, -v155, v156, 1.0
	v_fmac_f32_e32 v156, v157, v156
	v_div_scale_f32 v157, vcc, 1.0, v154, 1.0
	v_mul_f32_e32 v158, v157, v156
	v_fma_f32 v159, -v155, v158, v157
	v_fmac_f32_e32 v158, v159, v156
	v_fma_f32 v157, -v155, v158, v157
	s_nop 1
	v_div_fmas_f32 v157, v157, v156, v158
	v_div_fixup_f32 v157, v157, v154, 1.0
	v_mov_b32_e32 v156, v157
	v_pk_fma_f32 v[212:213], v[156:157], v[212:213], v[66:67] op_sel_hi:[0,1,1] neg_lo:[0,0,1] neg_hi:[0,0,1]
	v_pk_fma_f32 v[214:215], v[156:157], v[214:215], v[68:69] op_sel_hi:[0,1,1] neg_lo:[0,0,1] neg_hi:[0,0,1]
	v_pk_fma_f32 v[216:217], v[156:157], v[216:217], v[70:71] op_sel_hi:[0,1,1] neg_lo:[0,0,1] neg_hi:[0,0,1]
	v_pk_fma_f32 v[218:219], v[156:157], v[218:219], v[72:73] op_sel_hi:[0,1,1] neg_lo:[0,0,1] neg_hi:[0,0,1]
	s_nop 0
	v_cvt_pk_bf16_f32 v220, v212, v213
	v_cvt_pk_bf16_f32 v221, v214, v215
	v_cvt_pk_bf16_f32 v222, v216, v217
	v_cvt_pk_bf16_f32 v223, v218, v219
	s_add_u32 s2, s12, 0
	s_mul_i32 s2, s2, 0xc00
	v_add_u32_e32 v246, s2, v244
	global_store_dwordx4 v246, v[220:223], s[36:37] offset:2048
	v_mov_b32_e32 v212, 0
	v_mov_b32_e32 v213, 0
	v_mov_b32_e32 v214, 0
	v_mov_b32_e32 v215, 0
	v_mov_b32_e32 v216, 0
	v_mov_b32_e32 v217, 0
	v_mov_b32_e32 v218, 0
	v_mov_b32_e32 v219, 0
	s_add_i32 s15, s14, -7
	s_cmp_lt_u32 s15, s13
	s_cbranch_scc0 .Lp2_rw36
	s_mov_b64 exec, s[38:39]
	v_add_f32_e32 v212, v212, v10
	v_add_f32_e32 v213, v213, v11
	v_add_f32_e32 v214, v214, v12
	v_add_f32_e32 v215, v215, v13
	v_add_f32_e32 v216, v216, v14
	v_add_f32_e32 v217, v217, v15
	v_add_f32_e32 v218, v218, v16
	v_add_f32_e32 v219, v219, v17

.Lp2_rw38:
	s_add_i32 s15, s14, -4
	s_cmp_lt_u32 s15, s13
	s_cbranch_scc0 .Lp2_rw39
	s_mov_b64 exec, s[38:39]
	v_add_f32_e32 v212, v212, v34
	v_add_f32_e32 v213, v213, v35
	v_add_f32_e32 v214, v214, v36
	v_add_f32_e32 v215, v215, v37
	v_add_f32_e32 v216, v216, v38
	v_add_f32_e32 v217, v217, v39
	v_add_f32_e32 v218, v218, v40
	v_add_f32_e32 v219, v219, v41

.Lp2_rw40:
	s_add_i32 s15, s14, -2
	s_cmp_lt_u32 s15, s13
	s_cbranch_scc0 .Lp2_rw41
	s_mov_b64 exec, s[10:11]
	v_add_f32_e32 v212, v212, v50
	v_add_f32_e32 v213, v213, v51
	v_add_f32_e32 v214, v214, v52
	v_add_f32_e32 v215, v215, v53
	v_add_f32_e32 v216, v216, v54
	v_add_f32_e32 v217, v217, v55
	v_add_f32_e32 v218, v218, v56
	v_add_f32_e32 v219, v219, v57
.Lp2_rw41:
	s_add_i32 s15, s14, -1
	s_cmp_lt_u32 s15, s13
	s_cbranch_scc0 .Lp2_rw42
	s_mov_b64 exec, s[8:9]
	v_add_f32_e32 v212, v212, v58
	v_add_f32_e32 v213, v213, v59
	v_add_f32_e32 v214, v214, v60
	v_add_f32_e32 v215, v215, v61
	v_add_f32_e32 v216, v216, v62
	v_add_f32_e32 v217, v217, v63
	v_add_f32_e32 v218, v218, v64
	v_add_f32_e32 v219, v219, v65

.Lp2_rw43:
	s_add_i32 s15, s14, 1
	s_cmp_lt_u32 s15, s13
	s_cbranch_scc0 .Lp2_rw44
	s_mov_b64 exec, -1
	v_add_f32_e32 v212, v212, v74
	v_add_f32_e32 v213, v213, v75
	v_add_f32_e32 v214, v214, v76
	v_add_f32_e32 v215, v215, v77
	v_add_f32_e32 v216, v216, v78
	v_add_f32_e32 v217, v217, v79
	v_add_f32_e32 v218, v218, v80
	v_add_f32_e32 v219, v219, v81
.Lp2_rw44:
	s_add_i32 s15, s14, 2
	s_cmp_lt_u32 s15, s13
	s_cbranch_scc0 .Lp2_rw45
	s_mov_b64 exec, s[8:9]
	v_add_f32_e32 v212, v212, v82
	v_add_f32_e32 v213, v213, v83
	v_add_f32_e32 v214, v214, v84
	v_add_f32_e32 v215, v215, v85
	v_add_f32_e32 v216, v216, v86
	v_add_f32_e32 v217, v217, v87
	v_add_f32_e32 v218, v218, v88
	v_add_f32_e32 v219, v219, v89

.Lp2_rw46:
	s_add_i32 s15, s14, 4
	s_cmp_lt_u32 s15, s13
	s_cbranch_scc0 .Lp2_rw47
	s_mov_b64 exec, s[10:11]
	v_add_f32_e32 v212, v212, v98
	v_add_f32_e32 v213, v213, v99
	v_add_f32_e32 v214, v214, v100
	v_add_f32_e32 v215, v215, v101
	v_add_f32_e32 v216, v216, v102
	v_add_f32_e32 v217, v217, v103
	v_add_f32_e32 v218, v218, v104
	v_add_f32_e32 v219, v219, v105

.Lp2_rw50:
	s_add_i32 s15, s14, 8
	s_cmp_lt_u32 s15, s13
	s_cbranch_scc0 .Lp2_rw51
	s_mov_b64 exec, s[38:39]
	v_add_f32_e32 v212, v212, v130
	v_add_f32_e32 v213, v213, v131
	v_add_f32_e32 v214, v214, v132
	v_add_f32_e32 v215, v215, v133
	v_add_f32_e32 v216, v216, v134
	v_add_f32_e32 v217, v217, v135
	v_add_f32_e32 v218, v218, v136
	v_add_f32_e32 v219, v219, v137
.Lp2_rw51:
	s_mov_b64 exec, -1
	s_add_i32 s15, s14, 1
	v_sub_u32_e32 v247, s15, v245
	v_max_i32_e32 v247, 0, v247
	v_add_u32_e32 v248, s15, v245
	v_min_i32_e32 v248, s13, v248
	v_sub_u32_e32 v249, v248, v247
	v_cvt_f32_i32_e32 v154, v249
	v_div_scale_f32 v155, s[2:3], v154, v154, 1.0
	v_rcp_f32_e32 v156, v155
	s_nop 0
	v_fma_f32 v157, -v155, v156, 1.0
	v_fmac_f32_e32 v156, v157, v156
	v_div_scale_f32 v157, vcc, 1.0, v154, 1.0
	v_mul_f32_e32 v158, v157, v156
	v_fma_f32 v159, -v155, v158, v157
	v_fmac_f32_e32 v158, v159, v156
	v_fma_f32 v157, -v155, v158, v157
	s_nop 1
	v_div_fmas_f32 v157, v157, v156, v158
	v_div_fixup_f32 v157, v157, v154, 1.0
	v_mov_b32_e32 v156, v157
	v_pk_fma_f32 v[212:213], v[156:157], v[212:213], v[74:75] op_sel_hi:[0,1,1] neg_lo:[0,0,1] neg_hi:[0,0,1]
	v_pk_fma_f32 v[214:215], v[156:157], v[214:215], v[76:77] op_sel_hi:[0,1,1] neg_lo:[0,0,1] neg_hi:[0,0,1]
	v_pk_fma_f32 v[216:217], v[156:157], v[216:217], v[78:79] op_sel_hi:[0,1,1] neg_lo:[0,0,1] neg_hi:[0,0,1]
	v_pk_fma_f32 v[218:219], v[156:157], v[218:219], v[80:81] op_sel_hi:[0,1,1] neg_lo:[0,0,1] neg_hi:[0,0,1]
	s_nop 0
	v_cvt_pk_bf16_f32 v220, v212, v213
	v_cvt_pk_bf16_f32 v221, v214, v215
	v_cvt_pk_bf16_f32 v222, v216, v217
	v_cvt_pk_bf16_f32 v223, v218, v219
	s_add_u32 s2, s12, 1
	s_mul_i32 s2, s2, 0xc00
	v_add_u32_e32 v246, s2, v244
	global_store_dwordx4 v246, v[220:223], s[36:37] offset:2048
	v_mov_b32_e32 v212, 0
	v_mov_b32_e32 v213, 0
	v_mov_b32_e32 v214, 0
	v_mov_b32_e32 v215, 0
	v_mov_b32_e32 v216, 0
	v_mov_b32_e32 v217, 0
	v_mov_b32_e32 v218, 0
	v_mov_b32_e32 v219, 0
	s_add_i32 s15, s14, -6
	s_cmp_lt_u32 s15, s13
	s_cbranch_scc0 .Lp2_rw52
	s_mov_b64 exec, s[38:39]
	v_add_f32_e32 v212, v212, v18
	v_add_f32_e32 v213, v213, v19
	v_add_f32_e32 v214, v214, v20
	v_add_f32_e32 v215, v215, v21
	v_add_f32_e32 v216, v216, v22
	v_add_f32_e32 v217, v217, v23
	v_add_f32_e32 v218, v218, v24
	v_add_f32_e32 v219, v219, v25

.Lp2_rw54:
	s_add_i32 s15, s14, -3
	s_cmp_lt_u32 s15, s13
	s_cbranch_scc0 .Lp2_rw55
	s_mov_b64 exec, s[38:39]
	v_add_f32_e32 v212, v212, v42
	v_add_f32_e32 v213, v213, v43
	v_add_f32_e32 v214, v214, v44
	v_add_f32_e32 v215, v215, v45
	v_add_f32_e32 v216, v216, v46
	v_add_f32_e32 v217, v217, v47
	v_add_f32_e32 v218, v218, v48
	v_add_f32_e32 v219, v219, v49

.Lp2_rw56:
	s_add_i32 s15, s14, -1
	s_cmp_lt_u32 s15, s13
	s_cbranch_scc0 .Lp2_rw57
	s_mov_b64 exec, s[10:11]
	v_add_f32_e32 v212, v212, v58
	v_add_f32_e32 v213, v213, v59
	v_add_f32_e32 v214, v214, v60
	v_add_f32_e32 v215, v215, v61
	v_add_f32_e32 v216, v216, v62
	v_add_f32_e32 v217, v217, v63
	v_add_f32_e32 v218, v218, v64
	v_add_f32_e32 v219, v219, v65
.Lp2_rw57:
	s_add_i32 s15, s14, 0
	s_cmp_lt_u32 s15, s13
	s_cbranch_scc0 .Lp2_rw58
	s_mov_b64 exec, s[8:9]
	v_add_f32_e32 v212, v212, v66
	v_add_f32_e32 v213, v213, v67
	v_add_f32_e32 v214, v214, v68
	v_add_f32_e32 v215, v215, v69
	v_add_f32_e32 v216, v216, v70
	v_add_f32_e32 v217, v217, v71
	v_add_f32_e32 v218, v218, v72
	v_add_f32_e32 v219, v219, v73

.Lp2_rw59:
	s_add_i32 s15, s14, 2
	s_cmp_lt_u32 s15, s13
	s_cbranch_scc0 .Lp2_rw60
	s_mov_b64 exec, -1
	v_add_f32_e32 v212, v212, v82
	v_add_f32_e32 v213, v213, v83
	v_add_f32_e32 v214, v214, v84
	v_add_f32_e32 v215, v215, v85
	v_add_f32_e32 v216, v216, v86
	v_add_f32_e32 v217, v217, v87
	v_add_f32_e32 v218, v218, v88
	v_add_f32_e32 v219, v219, v89
.Lp2_rw60:
	s_add_i32 s15, s14, 3
	s_cmp_lt_u32 s15, s13
	s_cbranch_scc0 .Lp2_rw61
	s_mov_b64 exec, s[8:9]
	v_add_f32_e32 v212, v212, v90
	v_add_f32_e32 v213, v213, v91
	v_add_f32_e32 v214, v214, v92
	v_add_f32_e32 v215, v215, v93
	v_add_f32_e32 v216, v216, v94
	v_add_f32_e32 v217, v217, v95
	v_add_f32_e32 v218, v218, v96
	v_add_f32_e32 v219, v219, v97

.Lp2_rw62:
	s_add_i32 s15, s14, 5
	s_cmp_lt_u32 s15, s13
	s_cbranch_scc0 .Lp2_rw63
	s_mov_b64 exec, s[10:11]
	v_add_f32_e32 v212, v212, v106
	v_add_f32_e32 v213, v213, v107
	v_add_f32_e32 v214, v214, v108
	v_add_f32_e32 v215, v215, v109
	v_add_f32_e32 v216, v216, v110
	v_add_f32_e32 v217, v217, v111
	v_add_f32_e32 v218, v218, v112
	v_add_f32_e32 v219, v219, v113

.Lp2_rw66:
	s_add_i32 s15, s14, 9
	s_cmp_lt_u32 s15, s13
	s_cbranch_scc0 .Lp2_rw67
	s_mov_b64 exec, s[38:39]
	v_add_f32_e32 v212, v212, v138
	v_add_f32_e32 v213, v213, v139
	v_add_f32_e32 v214, v214, v140
	v_add_f32_e32 v215, v215, v141
	v_add_f32_e32 v216, v216, v142
	v_add_f32_e32 v217, v217, v143
	v_add_f32_e32 v218, v218, v144
	v_add_f32_e32 v219, v219, v145
.Lp2_rw67:
	s_mov_b64 exec, -1
	s_add_i32 s15, s14, 2
	v_sub_u32_e32 v247, s15, v245
	v_max_i32_e32 v247, 0, v247
	v_add_u32_e32 v248, s15, v245
	v_min_i32_e32 v248, s13, v248
	v_sub_u32_e32 v249, v248, v247
	v_cvt_f32_i32_e32 v154, v249
	v_div_scale_f32 v155, s[2:3], v154, v154, 1.0
	v_rcp_f32_e32 v156, v155
	s_nop 0
	v_fma_f32 v157, -v155, v156, 1.0
	v_fmac_f32_e32 v156, v157, v156
	v_div_scale_f32 v157, vcc, 1.0, v154, 1.0
	v_mul_f32_e32 v158, v157, v156
	v_fma_f32 v159, -v155, v158, v157
	v_fmac_f32_e32 v158, v159, v156
	v_fma_f32 v157, -v155, v158, v157
	s_nop 1
	v_div_fmas_f32 v157, v157, v156, v158
	v_div_fixup_f32 v157, v157, v154, 1.0
	v_mov_b32_e32 v156, v157
	v_pk_fma_f32 v[212:213], v[156:157], v[212:213], v[82:83] op_sel_hi:[0,1,1] neg_lo:[0,0,1] neg_hi:[0,0,1]
	v_pk_fma_f32 v[214:215], v[156:157], v[214:215], v[84:85] op_sel_hi:[0,1,1] neg_lo:[0,0,1] neg_hi:[0,0,1]
	v_pk_fma_f32 v[216:217], v[156:157], v[216:217], v[86:87] op_sel_hi:[0,1,1] neg_lo:[0,0,1] neg_hi:[0,0,1]
	v_pk_fma_f32 v[218:219], v[156:157], v[218:219], v[88:89] op_sel_hi:[0,1,1] neg_lo:[0,0,1] neg_hi:[0,0,1]
	s_nop 0
	v_cvt_pk_bf16_f32 v220, v212, v213
	v_cvt_pk_bf16_f32 v221, v214, v215
	v_cvt_pk_bf16_f32 v222, v216, v217
	v_cvt_pk_bf16_f32 v223, v218, v219
	s_add_u32 s2, s12, 2
	s_mul_i32 s2, s2, 0xc00
	v_add_u32_e32 v246, s2, v244
	global_store_dwordx4 v246, v[220:223], s[36:37] offset:2048
	v_mov_b32_e32 v212, 0
	v_mov_b32_e32 v213, 0
	v_mov_b32_e32 v214, 0
	v_mov_b32_e32 v215, 0
	v_mov_b32_e32 v216, 0
	v_mov_b32_e32 v217, 0
	v_mov_b32_e32 v218, 0
	v_mov_b32_e32 v219, 0
	s_add_i32 s15, s14, -5
	s_cmp_lt_u32 s15, s13
	s_cbranch_scc0 .Lp2_rw68
	s_mov_b64 exec, s[38:39]
	v_add_f32_e32 v212, v212, v26
	v_add_f32_e32 v213, v213, v27
	v_add_f32_e32 v214, v214, v28
	v_add_f32_e32 v215, v215, v29
	v_add_f32_e32 v216, v216, v30
	v_add_f32_e32 v217, v217, v31
	v_add_f32_e32 v218, v218, v32
	v_add_f32_e32 v219, v219, v33

.Lp2_rw70:
	s_add_i32 s15, s14, -2
	s_cmp_lt_u32 s15, s13
	s_cbranch_scc0 .Lp2_rw71
	s_mov_b64 exec, s[38:39]
	v_add_f32_e32 v212, v212, v50
	v_add_f32_e32 v213, v213, v51
	v_add_f32_e32 v214, v214, v52
	v_add_f32_e32 v215, v215, v53
	v_add_f32_e32 v216, v216, v54
	v_add_f32_e32 v217, v217, v55
	v_add_f32_e32 v218, v218, v56
	v_add_f32_e32 v219, v219, v57

.Lp2_rw72:
	s_add_i32 s15, s14, 0
	s_cmp_lt_u32 s15, s13
	s_cbranch_scc0 .Lp2_rw73
	s_mov_b64 exec, s[10:11]
	v_add_f32_e32 v212, v212, v66
	v_add_f32_e32 v213, v213, v67
	v_add_f32_e32 v214, v214, v68
	v_add_f32_e32 v215, v215, v69
	v_add_f32_e32 v216, v216, v70
	v_add_f32_e32 v217, v217, v71
	v_add_f32_e32 v218, v218, v72
	v_add_f32_e32 v219, v219, v73

.Lp2_rw75:
	s_add_i32 s15, s14, 3
	s_cmp_lt_u32 s15, s13
	s_cbranch_scc0 .Lp2_rw76
	s_mov_b64 exec, -1
	v_add_f32_e32 v212, v212, v90
	v_add_f32_e32 v213, v213, v91
	v_add_f32_e32 v214, v214, v92
	v_add_f32_e32 v215, v215, v93
	v_add_f32_e32 v216, v216, v94
	v_add_f32_e32 v217, v217, v95
	v_add_f32_e32 v218, v218, v96
	v_add_f32_e32 v219, v219, v97
.Lp2_rw76:
	s_add_i32 s15, s14, 4
	s_cmp_lt_u32 s15, s13
	s_cbranch_scc0 .Lp2_rw77
	s_mov_b64 exec, s[8:9]
	v_add_f32_e32 v212, v212, v98
	v_add_f32_e32 v213, v213, v99
	v_add_f32_e32 v214, v214, v100
	v_add_f32_e32 v215, v215, v101
	v_add_f32_e32 v216, v216, v102
	v_add_f32_e32 v217, v217, v103
	v_add_f32_e32 v218, v218, v104
	v_add_f32_e32 v219, v219, v105

.Lp2_rw78:
	s_add_i32 s15, s14, 6
	s_cmp_lt_u32 s15, s13
	s_cbranch_scc0 .Lp2_rw79
	s_mov_b64 exec, s[10:11]
	v_add_f32_e32 v212, v212, v114
	v_add_f32_e32 v213, v213, v115
	v_add_f32_e32 v214, v214, v116
	v_add_f32_e32 v215, v215, v117
	v_add_f32_e32 v216, v216, v118
	v_add_f32_e32 v217, v217, v119
	v_add_f32_e32 v218, v218, v120
	v_add_f32_e32 v219, v219, v121

.Lp2_rw82:
	s_add_i32 s15, s14, 10
	s_cmp_lt_u32 s15, s13
	s_cbranch_scc0 .Lp2_rw83
	s_mov_b64 exec, s[38:39]
	v_add_f32_e32 v212, v212, v146
	v_add_f32_e32 v213, v213, v147
	v_add_f32_e32 v214, v214, v148
	v_add_f32_e32 v215, v215, v149
	v_add_f32_e32 v216, v216, v150
	v_add_f32_e32 v217, v217, v151
	v_add_f32_e32 v218, v218, v152
	v_add_f32_e32 v219, v219, v153
